# out-proj: next tile's first K step requested before the epilogue into the free LDS stage, LDS->LDS copy at the next tile's start
# baseline (speedup 1.0000x reference)
.LBB0_70:
.LBB0_71:
	v_readlane_b32 s0, v253, 43
	v_readlane_b32 s1, v253, 44
	s_andn2_b64 vcc, exec, s[0:1]
	s_cbranch_vccnz .LBB0_90
	v_mov_b32_e32 v0, v151
	s_ashr_i32 s81, s80, 31
	s_lshl_b64 s[0:1], s[80:81], 21
	v_readlane_b32 s5, v253, 28
	s_add_u32 s5, s5, s0
	v_readlane_b32 s6, v253, 29
	v_readlane_b32 s9, v254, 7
	s_addc_u32 s6, s6, s1
	s_mov_b32 s7, s9
	v_mov_b32_e32 v149, 0
	v_readlane_b32 s8, v255, 34
	s_branch .LBB0_74
.LBB0_73:
	s_cmpk_gt_i32 s9, 0x7f
	s_cbranch_scc1 .Lop_nopf
	s_add_u32 s48, s48, 0x1000000
	s_addc_u32 s49, s49, 0
	v_add_u32_e32 v185, 0xfffff800, v185
	v_add_u32_e32 v188, 0xfffff800, v188
	v_add_u32_e32 v193, 0xfffff800, v193
	v_add_u32_e32 v194, 0xfffff800, v194
	v_readfirstlane_b32 s12, v122
	s_nop 0
	s_add_u32 m0, s12, 0x9000
	s_nop 0
	global_load_lds_dwordx4 v185, s[48:49]
	s_add_u32 m0, s12, 0xd000
	s_nop 0
	global_load_lds_dwordx4 v185, s[100:101]
	s_add_u32 m0, s12, 0x9400
	s_nop 0
	global_load_lds_dwordx4 v188, s[48:49]
	s_add_u32 m0, s12, 0xd400
	s_nop 0
	global_load_lds_dwordx4 v188, s[100:101]
	s_add_u32 m0, s12, 0x9800
	s_nop 0
	global_load_lds_dwordx4 v193, s[48:49]
	s_add_u32 m0, s12, 0xd800
	s_nop 0
	global_load_lds_dwordx4 v193, s[100:101]
	s_add_u32 m0, s12, 0x9c00
	s_nop 0
	global_load_lds_dwordx4 v194, s[48:49]
	s_add_u32 m0, s12, 0xdc00
	s_nop 0
	global_load_lds_dwordx4 v194, s[100:101]
	v_mov_b32_e32 v149, 1

.LBB0_74:
	s_and_b32 s10, s8, 0xffffe00
	v_readlane_b32 s13, v253, 45
	s_or_b32 s10, s13, s10
	s_and_b32 s12, s9, 56
	s_add_i32 s10, s10, s12
	s_lshl_b32 s10, s10, 4
	v_mov_b32_e32 v8, v151
	s_ashr_i32 s11, s10, 31
	s_lshl_b64 s[40:41], s[10:11], 1
	v_bfe_u32 v12, v8, 4, 2
	s_and_b32 s10, s7, 7
	v_and_b32_e32 v9, 63, v8
	v_ashrrev_i32_e32 v11, 6, v8
	v_xor_b32_e32 v0, v12, v8
	s_lshl_b32 s11, s10, 18
	s_lshl_b32 s10, s9, 3
	v_lshl_or_b32 v3, v11, 8, v9
	v_lshlrev_b32_e32 v0, 3, v0
	s_and_b32 s10, s10, 0xfffffe00
	s_or_b32 s12, s12, s13
	v_lshlrev_b32_e32 v2, 7, v3
	v_and_b32_e32 v13, 56, v0
	s_movk_i32 s42, 0x9c00
	s_or_b32 s10, s12, s10
	v_and_or_b32 v0, v2, s42, v13
	v_or_b32_e32 v2, 64, v3
	s_ashr_i32 s12, s10, 3
	v_lshrrev_b32_e32 v4, 4, v2
	s_ashr_i32 s13, s12, 31
	v_xor_b32_e32 v4, v4, v8
	v_or_b32_e32 v3, 0xc0, v3
	s_and_b32 s10, s9, 7
	s_lshl_b64 s[28:29], s[12:13], 17
	s_lshl_b64 s[38:39], s[12:13], 18
	v_lshlrev_b32_e32 v14, 7, v2
	v_lshlrev_b32_e32 v2, 3, v4
	v_lshrrev_b32_e32 v4, 4, v3
	s_add_u32 s12, s94, s38
	v_xor_b32_e32 v4, v4, v8
	v_lshlrev_b32_e32 v122, 12, v11
	s_addc_u32 s13, s95, s39
	s_lshl_b32 s14, s10, 18
	v_lshlrev_b32_e32 v16, 7, v3
	v_lshlrev_b32_e32 v3, 3, v4
	v_lshlrev_b64 v[4:5], 1, v[0:1]
	v_readfirstlane_b32 s16, v122
	v_add_u32_e32 v123, 0x4000, v122
	s_add_u32 s14, s5, s14
	v_lshl_add_u64 v[6:7], s[12:13], 0, v[4:5]
	s_mov_b32 m0, s16
	v_readfirstlane_b32 s16, v123
	s_addc_u32 s15, s6, 0
	v_and_b32_e32 v15, 56, v2
	s_mov_b64 s[48:49], s[12:13]
	s_mov_b64 s[100:101], s[14:15]
	v_and_b32_e32 v250, 63, v151
	v_lshrrev_b32_e32 v251, 4, v250
	v_and_b32_e32 v185, 7, v250
	v_xor_b32_e32 v185, v185, v251
	v_lshlrev_b32_e32 v185, 4, v185
	v_lshrrev_b32_e32 v251, 3, v250
	v_lshl_or_b32 v185, v251, 11, v185
	v_lshrrev_b32_e32 v251, 6, v151
	v_lshl_add_u32 v185, v251, 16, v185
	v_add_u32_e32 v185, 0x80, v185
	v_xor_b32_e32 v188, 64, v185
	v_add_u32_e32 v188, 0x4000, v188
	v_add_u32_e32 v193, 0x8000, v185
	v_add_u32_e32 v194, 0x8000, v188
	v_readfirstlane_b32 s17, v149
	s_cmp_lg_u32 s17, 0
	s_cbranch_scc1 .Lop_pf_pre
	s_barrier
	global_load_lds_dwordx4 v[6:7], off
	s_mov_b32 m0, s16
	s_movk_i32 s16, 0xbc00
	v_or_b32_e32 v2, 0x4000, v0
	v_lshl_add_u64 v[4:5], s[14:15], 0, v[4:5]
	v_and_or_b32 v0, v14, s16, v15
	global_load_lds_dwordx4 v[4:5], off
	v_lshlrev_b64 v[4:5], 1, v[0:1]
	v_or_b32_e32 v0, 0x400, v122
	v_add_u32_e32 v124, 0x4400, v122
	v_readfirstlane_b32 s16, v0
	v_and_b32_e32 v17, 56, v3
	v_lshl_add_u64 v[6:7], s[12:13], 0, v[4:5]
	s_mov_b32 m0, s16
	v_readfirstlane_b32 s16, v124
	v_mov_b32_e32 v3, v1
	v_or_b32_e32 v0, 0x800, v122
	global_load_lds_dwordx4 v[6:7], off
	v_lshl_add_u64 v[6:7], s[14:15], 0, v[4:5]
	s_mov_b32 m0, s16
	v_lshlrev_b64 v[2:3], 1, v[2:3]
	v_readfirstlane_b32 s16, v0
	v_add_u32_e32 v125, 0x4800, v122
	global_load_lds_dwordx4 v[6:7], off
	v_lshl_add_u64 v[6:7], s[12:13], 0, v[2:3]
	s_mov_b32 m0, s16
	v_readfirstlane_b32 s16, v125
	global_load_lds_dwordx4 v[6:7], off
	s_mov_b32 m0, s16
	v_readlane_b32 s16, v255, 35
	v_readlane_b32 s17, v255, 36
	s_movk_i32 s17, 0xfc00
	v_lshl_add_u64 v[2:3], s[14:15], 0, v[2:3]
	v_and_or_b32 v0, v16, s17, v17
	global_load_lds_dwordx4 v[2:3], off
	v_lshlrev_b64 v[2:3], 1, v[0:1]
	v_or_b32_e32 v0, 0xc00, v122
	v_lshl_add_u64 v[6:7], s[12:13], 0, v[2:3]
	v_readfirstlane_b32 s12, v0
	v_add_u32_e32 v126, 0x4c00, v122
	s_mov_b32 m0, s12
	v_readfirstlane_b32 s12, v126
	global_load_lds_dwordx4 v[6:7], off
	v_lshl_add_u64 v[6:7], s[14:15], 0, v[2:3]
	s_mov_b32 m0, s12
	v_lshrrev_b32_e32 v0, 1, v8
	global_load_lds_dwordx4 v[6:7], off
	s_branch .Lop_pf_join
.Lop_pf_pre:
	v_mov_b32_e32 v149, 0
	s_waitcnt vmcnt(0)
	s_barrier
	s_movk_i32 s16, 0xbc00
	v_or_b32_e32 v2, 0x4000, v0
	v_lshl_add_u64 v[4:5], s[14:15], 0, v[4:5]
	v_and_or_b32 v0, v14, s16, v15
	v_lshlrev_b64 v[4:5], 1, v[0:1]
	v_or_b32_e32 v0, 0x400, v122
	v_add_u32_e32 v124, 0x4400, v122
	v_and_b32_e32 v17, 56, v3
	v_lshl_add_u64 v[6:7], s[12:13], 0, v[4:5]
	v_mov_b32_e32 v3, v1
	v_or_b32_e32 v0, 0x800, v122
	v_lshl_add_u64 v[6:7], s[14:15], 0, v[4:5]
	v_lshlrev_b64 v[2:3], 1, v[2:3]
	v_add_u32_e32 v125, 0x4800, v122
	v_lshl_add_u64 v[6:7], s[12:13], 0, v[2:3]
	v_readlane_b32 s16, v255, 35
	v_readlane_b32 s17, v255, 36
	s_movk_i32 s17, 0xfc00
	v_lshl_add_u64 v[2:3], s[14:15], 0, v[2:3]
	v_and_or_b32 v0, v16, s17, v17
	v_lshlrev_b64 v[2:3], 1, v[0:1]
	v_or_b32_e32 v0, 0xc00, v122
	v_lshl_add_u64 v[6:7], s[12:13], 0, v[2:3]
	v_add_u32_e32 v126, 0x4c00, v122
	v_lshl_add_u64 v[6:7], s[14:15], 0, v[2:3]
	v_lshrrev_b32_e32 v0, 1, v8
	v_lshlrev_b32_e32 v250, 4, v151
	v_add_u32_e32 v251, 0x9000, v250
	ds_read_b128 v[90:93], v251 offset:0
	ds_read_b128 v[94:97], v251 offset:4096
	ds_read_b128 v[98:101], v251 offset:8192
	ds_read_b128 v[102:105], v251 offset:12288
	s_waitcnt lgkmcnt(3)
	ds_write_b128 v250, v[90:93] offset:0
	s_waitcnt lgkmcnt(2)
	ds_write_b128 v250, v[94:97] offset:4096
	s_waitcnt lgkmcnt(1)
	ds_write_b128 v250, v[98:101] offset:8192
	s_waitcnt lgkmcnt(0)
	ds_write_b128 v250, v[102:105] offset:12288
	ds_read_b128 v[90:93], v251 offset:16384
	ds_read_b128 v[94:97], v251 offset:20480
	ds_read_b128 v[98:101], v251 offset:24576
	ds_read_b128 v[102:105], v251 offset:28672
	s_waitcnt lgkmcnt(3)
	ds_write_b128 v250, v[90:93] offset:16384
	s_waitcnt lgkmcnt(2)
	ds_write_b128 v250, v[94:97] offset:20480
	s_waitcnt lgkmcnt(1)
	ds_write_b128 v250, v[98:101] offset:24576
	s_waitcnt lgkmcnt(0)
	ds_write_b128 v250, v[102:105] offset:28672
	s_waitcnt lgkmcnt(0)
.Lop_pf_join:
	v_ashrrev_i32_e32 v10, 7, v8
	v_bitop3_b32 v0, v12, v0, 7 bitop3:0x78
	v_lshlrev_b32_e32 v16, 13, v11
	v_bfe_u32 v6, v8, 1, 3
	v_lshlrev_b32_e32 v0, 4, v0
	v_lshlrev_b32_e32 v7, 13, v10
	v_and_b32_e32 v16, 0x2000, v16
	v_or_b32_e32 v15, v0, v7
	v_or_b32_e32 v17, v0, v16
	v_bitop3_b32 v0, v12, v6, 4 bitop3:0x36
	v_lshlrev_b32_e32 v6, 3, v8
	v_lshlrev_b32_e32 v0, 4, v0
	v_and_b32_e32 v6, 0x78, v6
	v_or_b32_e32 v12, v0, v7
	v_add_u32_e32 v7, 0x100, v8
	s_waitcnt vmcnt(0)
	v_lshlrev_b32_e32 v24, 7, v6
	v_or_b32_e32 v27, 2, v6
	v_or_b32_e32 v30, 3, v6
	v_or_b32_e32 v33, 4, v6
	v_or_b32_e32 v36, 5, v6
	v_or_b32_e32 v39, 6, v6
	v_or_b32_e32 v6, 7, v6
	v_ashrrev_i32_e32 v18, 4, v7
	v_lshlrev_b32_e32 v25, 2, v8
	v_lshlrev_b32_e32 v28, 7, v27
	v_lshrrev_b32_e32 v27, 1, v27
	v_lshlrev_b32_e32 v31, 7, v30
	v_lshrrev_b32_e32 v30, 1, v30
	v_lshlrev_b32_e32 v34, 7, v33
	v_lshrrev_b32_e32 v33, 1, v33
	v_lshlrev_b32_e32 v37, 7, v36
	v_lshrrev_b32_e32 v36, 1, v36
	v_lshlrev_b32_e32 v40, 7, v39
	v_lshrrev_b32_e32 v39, 1, v39
	v_lshlrev_b32_e32 v42, 7, v6
	v_lshrrev_b32_e32 v6, 1, v6
	v_ashrrev_i32_e32 v7, 7, v7
	v_add_u32_e32 v19, 0x200, v8
	v_bitop3_b32 v43, v25, v7, 4 bitop3:0x6c
	v_bitop3_b32 v44, v27, v7, 5 bitop3:0x6c
	v_bitop3_b32 v45, v30, v7, 5 bitop3:0x6c
	v_bitop3_b32 v46, v33, v7, 6 bitop3:0x6c
	v_bitop3_b32 v47, v36, v7, 6 bitop3:0x6c
	v_bitop3_b32 v48, v39, v7, 7 bitop3:0x6c
	v_bitop3_b32 v7, v6, v7, 7 bitop3:0x6c
	v_lshl_add_u32 v49, v7, 4, v42
	v_ashrrev_i32_e32 v7, 7, v19
	v_ashrrev_i32_e32 v20, 4, v19
	v_add_u32_e32 v21, 0x300, v8
	v_bitop3_b32 v19, v25, v7, 4 bitop3:0x6c
	v_bitop3_b32 v50, v27, v7, 5 bitop3:0x6c
	v_bitop3_b32 v51, v30, v7, 5 bitop3:0x6c
	v_bitop3_b32 v52, v33, v7, 6 bitop3:0x6c
	v_bitop3_b32 v53, v36, v7, 6 bitop3:0x6c
	v_bitop3_b32 v54, v39, v7, 7 bitop3:0x6c
	v_bitop3_b32 v7, v6, v7, 7 bitop3:0x6c
	v_lshl_add_u32 v55, v7, 4, v42
	v_ashrrev_i32_e32 v7, 7, v21
	v_ashrrev_i32_e32 v22, 4, v21
	v_bitop3_b32 v26, v25, v10, 4 bitop3:0x6c
	v_bitop3_b32 v21, v25, v7, 4 bitop3:0x6c
	v_lshlrev_b32_e32 v14, 7, v8
	v_or_b32_e32 v16, v0, v16
	v_ashrrev_i32_e32 v0, 4, v8
	v_lshrrev_b32_e32 v23, 3, v8
	v_lshl_add_u32 v26, v26, 4, v24
	v_bitop3_b32 v29, v27, v10, 5 bitop3:0x6c
	v_bitop3_b32 v32, v30, v10, 5 bitop3:0x6c
	v_bitop3_b32 v35, v33, v10, 6 bitop3:0x6c
	v_bitop3_b32 v38, v36, v10, 6 bitop3:0x6c
	v_bitop3_b32 v41, v39, v10, 7 bitop3:0x6c
	v_bitop3_b32 v10, v6, v10, 7 bitop3:0x6c
	v_lshl_add_u32 v43, v43, 4, v24
	v_lshl_add_u32 v19, v19, 4, v24
	v_lshl_add_u32 v21, v21, 4, v24
	v_bitop3_b32 v24, v27, v7, 5 bitop3:0x6c
	v_bitop3_b32 v25, v30, v7, 5 bitop3:0x6c
	v_bitop3_b32 v6, v6, v7, 7 bitop3:0x6c
	s_mov_b32 s14, 0xc000
	v_lshlrev_b32_e32 v8, 4, v8
	v_lshl_add_u32 v29, v29, 4, v28
	v_lshl_add_u32 v32, v32, 4, v31
	v_lshl_add_u32 v44, v44, 4, v28
	v_lshl_add_u32 v45, v45, 4, v31
	v_lshl_add_u32 v50, v50, 4, v28
	v_lshl_add_u32 v51, v51, 4, v31
	v_lshl_add_u32 v24, v24, 4, v28
	v_lshl_add_u32 v25, v25, 4, v31
	v_bitop3_b32 v27, v33, v7, 6 bitop3:0x6c
	v_bitop3_b32 v28, v36, v7, 6 bitop3:0x6c
	v_bitop3_b32 v30, v39, v7, 7 bitop3:0x6c
	v_lshl_add_u32 v31, v6, 4, v42
	v_mad_i64_i32 v[6:7], s[12:13], v22, s14, 0
	v_and_b32_e32 v8, 0xf0, v8
	v_or_b32_e32 v6, v6, v8
	v_lshl_add_u64 v[82:83], v[6:7], 0, s[40:41]
	v_mad_i64_i32 v[6:7], s[12:13], v20, s14, 0
	v_or_b32_e32 v6, v6, v8
	v_lshl_add_u64 v[84:85], v[6:7], 0, s[40:41]
	v_mad_i64_i32 v[6:7], s[12:13], v18, s14, 0
	v_or_b32_e32 v6, v6, v8
	v_lshl_add_u64 v[86:87], v[6:7], 0, s[40:41]
	v_mad_i64_i32 v[6:7], s[12:13], v0, s14, 0
	v_lshlrev_b32_e32 v0, 7, v9
	v_or_b32_e32 v6, v6, v8
	v_lshl_or_b32 v0, v11, 15, v0
	v_lshl_add_u64 v[88:89], v[6:7], 0, s[40:41]
	v_and_or_b32 v6, v0, s42, v13
	s_waitcnt vmcnt(0)
	s_add_u32 s12, s0, s11
	v_or_b32_e32 v0, 0x4000, v6
	v_mov_b32_e32 v7, v1
	v_and_b32_e32 v14, 0x780, v14
	v_and_b32_e32 v23, 14, v23
	v_lshl_add_u32 v35, v35, 4, v34
	v_lshl_add_u32 v38, v38, 4, v37
	v_lshl_add_u32 v41, v41, 4, v40
	v_lshl_add_u32 v10, v10, 4, v42
	v_lshl_add_u32 v46, v46, 4, v34
	v_lshl_add_u32 v47, v47, 4, v37
	v_lshl_add_u32 v48, v48, 4, v40
	v_lshl_add_u32 v52, v52, 4, v34
	v_lshl_add_u32 v53, v53, 4, v37
	v_lshl_add_u32 v54, v54, 4, v40
	v_lshl_add_u32 v27, v27, 4, v34
	v_lshl_add_u32 v28, v28, 4, v37
	v_lshl_add_u32 v30, v30, 4, v40
	s_addc_u32 s13, s1, 0
	v_lshlrev_b64 v[8:9], 1, v[0:1]
	v_lshlrev_b64 v[6:7], 1, v[6:7]
	v_mov_b32_e32 v18, 0
	v_lshl_add_u64 v[90:91], s[12:13], 0, v[2:3]
	v_lshl_add_u64 v[92:93], s[12:13], 0, v[8:9]
	v_lshl_add_u64 v[94:95], s[12:13], 0, v[4:5]
	v_lshl_add_u64 v[96:97], s[12:13], 0, v[6:7]
	v_lshl_add_u64 v[98:99], s[38:39], 0, v[4:5]
	v_lshl_add_u64 v[100:101], s[38:39], 0, v[6:7]
	v_lshl_add_u64 v[102:103], s[38:39], 0, v[8:9]
	v_lshl_add_u64 v[104:105], s[38:39], 0, v[2:3]
	s_mov_b32 s11, 0
	v_add_u32_e32 v0, v15, v14
	v_add_u32_e32 v127, v17, v14
	v_add_u32_e32 v128, v12, v14
	v_add_u32_e32 v129, v16, v14
	v_add_u32_e32 v130, v26, v23
	v_add_u32_e32 v131, v29, v23
	v_add_u32_e32 v132, v32, v23
	v_add_u32_e32 v133, v35, v23
	v_add_u32_e32 v134, v38, v23
	v_add_u32_e32 v135, v41, v23
	v_add_u32_e32 v136, v10, v23
	v_add_u32_e32 v137, v43, v23
	v_add_u32_e32 v138, v44, v23
	v_add_u32_e32 v139, v45, v23
	v_add_u32_e32 v140, v46, v23
	v_add_u32_e32 v141, v47, v23
	v_add_u32_e32 v142, v48, v23
	v_add_u32_e32 v143, v49, v23
	v_add_u32_e32 v144, v19, v23
	v_add_u32_e32 v145, v50, v23
	v_add_u32_e32 v154, v51, v23
	v_add_u32_e32 v155, v52, v23
	v_add_u32_e32 v156, v53, v23
	v_add_u32_e32 v157, v54, v23
	v_add_u32_e32 v158, v55, v23
	v_add_u32_e32 v159, v21, v23
	v_add_u32_e32 v160, v24, v23
	v_add_u32_e32 v161, v25, v23
	v_add_u32_e32 v162, v27, v23
	v_add_u32_e32 v163, v28, v23
	v_add_u32_e32 v164, v30, v23
	v_add_u32_e32 v165, v31, v23
	v_and_b32_e32 v240, 15, v151
	v_lshrrev_b32_e32 v241, 4, v151
	v_sub_u32_e32 v242, v240, v241
	v_mul_i32_i24_e32 v244, 0xbff0, v242
	v_ashrrev_i32_e32 v245, 31, v244
	v_lshl_add_u64 v[82:83], v[82:83], 0, v[244:245]
	v_lshl_add_u64 v[84:85], v[84:85], 0, v[244:245]
	v_lshl_add_u64 v[86:87], v[86:87], 0, v[244:245]
	v_lshl_add_u64 v[88:89], v[88:89], 0, v[244:245]
	v_and_b32_e32 v246, 7, v240
	v_lshlrev_b32_e32 v246, 1, v246
	v_lshl_or_b32 v246, v241, 10, v246
	v_lshrrev_b32_e32 v247, 3, v240
	v_and_b32_e32 v242, 1, v241
	v_lshlrev_b32_e32 v242, 2, v242
	v_add_u32_e32 v243, 0, v247
	v_or_b32_e32 v248, 0, v242
	v_xor_b32_e32 v248, v243, v248
	v_lshl_add_u32 v130, v248, 4, v246
	v_or_b32_e32 v248, 1, v242
	v_xor_b32_e32 v248, v243, v248
	v_lshl_add_u32 v248, v248, 4, v246
	v_add_u32_e32 v131, 0x100, v248
	v_add_u32_e32 v132, 0x180, v248
	v_or_b32_e32 v248, 2, v242
	v_xor_b32_e32 v248, v243, v248
	v_lshl_add_u32 v248, v248, 4, v246
	v_add_u32_e32 v133, 0x200, v248
	v_add_u32_e32 v134, 0x280, v248
	v_or_b32_e32 v248, 3, v242
	v_xor_b32_e32 v248, v243, v248
	v_lshl_add_u32 v248, v248, 4, v246
	v_add_u32_e32 v135, 0x300, v248
	v_add_u32_e32 v136, 0x380, v248
	v_add_u32_e32 v243, 2, v247
	v_or_b32_e32 v248, 0, v242
	v_xor_b32_e32 v248, v243, v248
	v_lshl_add_u32 v137, v248, 4, v246
	v_or_b32_e32 v248, 1, v242
	v_xor_b32_e32 v248, v243, v248
	v_lshl_add_u32 v248, v248, 4, v246
	v_add_u32_e32 v138, 0x100, v248
	v_add_u32_e32 v139, 0x180, v248
	v_or_b32_e32 v248, 2, v242
	v_xor_b32_e32 v248, v243, v248
	v_lshl_add_u32 v248, v248, 4, v246
	v_add_u32_e32 v140, 0x200, v248
	v_add_u32_e32 v141, 0x280, v248
	v_or_b32_e32 v248, 3, v242
	v_xor_b32_e32 v248, v243, v248
	v_lshl_add_u32 v248, v248, 4, v246
	v_add_u32_e32 v142, 0x300, v248
	v_add_u32_e32 v143, 0x380, v248
	v_add_u32_e32 v243, 4, v247
	v_or_b32_e32 v248, 0, v242
	v_xor_b32_e32 v248, v243, v248
	v_lshl_add_u32 v144, v248, 4, v246
	v_or_b32_e32 v248, 1, v242
	v_xor_b32_e32 v248, v243, v248
	v_lshl_add_u32 v248, v248, 4, v246
	v_add_u32_e32 v145, 0x100, v248
	v_add_u32_e32 v154, 0x180, v248
	v_or_b32_e32 v248, 2, v242
	v_xor_b32_e32 v248, v243, v248
	v_lshl_add_u32 v248, v248, 4, v246
	v_add_u32_e32 v155, 0x200, v248
	v_add_u32_e32 v156, 0x280, v248
	v_or_b32_e32 v248, 3, v242
	v_xor_b32_e32 v248, v243, v248
	v_lshl_add_u32 v248, v248, 4, v246
	v_add_u32_e32 v157, 0x300, v248
	v_add_u32_e32 v158, 0x380, v248
	v_add_u32_e32 v243, 6, v247
	v_or_b32_e32 v248, 0, v242
	v_xor_b32_e32 v248, v243, v248
	v_lshl_add_u32 v159, v248, 4, v246
	v_or_b32_e32 v248, 1, v242
	v_xor_b32_e32 v248, v243, v248
	v_lshl_add_u32 v248, v248, 4, v246
	v_add_u32_e32 v160, 0x100, v248
	v_add_u32_e32 v161, 0x180, v248
	v_or_b32_e32 v248, 2, v242
	v_xor_b32_e32 v248, v243, v248
	v_lshl_add_u32 v248, v248, 4, v246
	v_add_u32_e32 v162, 0x200, v248
	v_add_u32_e32 v163, 0x280, v248
	v_or_b32_e32 v248, 3, v242
	v_xor_b32_e32 v248, v243, v248
	v_lshl_add_u32 v248, v248, 4, v246
	v_add_u32_e32 v164, 0x300, v248
	v_add_u32_e32 v165, 0x380, v248
	v_mov_b32_e32 v19, v18
	v_mov_b32_e32 v20, v18
	v_mov_b32_e32 v21, v18
	v_mov_b32_e32 v22, v18
	v_mov_b32_e32 v23, v18
	v_mov_b32_e32 v24, v18
	v_mov_b32_e32 v25, v18
	v_mov_b32_e32 v26, v18
	v_mov_b32_e32 v27, v18
	v_mov_b32_e32 v28, v18
	v_mov_b32_e32 v29, v18
	v_mov_b32_e32 v30, v18
	v_mov_b32_e32 v31, v18
	v_mov_b32_e32 v32, v18
	v_mov_b32_e32 v33, v18
	v_mov_b32_e32 v34, v18
	v_mov_b32_e32 v35, v18
	v_mov_b32_e32 v36, v18
	v_mov_b32_e32 v37, v18
	v_mov_b32_e32 v38, v18
	v_mov_b32_e32 v39, v18
	v_mov_b32_e32 v40, v18
	v_mov_b32_e32 v41, v18
	v_mov_b32_e32 v42, v18
	v_mov_b32_e32 v43, v18
	v_mov_b32_e32 v44, v18
	v_mov_b32_e32 v45, v18
	v_mov_b32_e32 v46, v18
	v_mov_b32_e32 v47, v18
	v_mov_b32_e32 v48, v18
	v_mov_b32_e32 v49, v18
	v_mov_b32_e32 v50, v18
	v_mov_b32_e32 v51, v18
	v_mov_b32_e32 v52, v18
	v_mov_b32_e32 v53, v18
	v_mov_b32_e32 v54, v18
	v_mov_b32_e32 v55, v18
	v_mov_b32_e32 v56, v18
	v_mov_b32_e32 v57, v18
	v_mov_b32_e32 v58, v18
	v_mov_b32_e32 v59, v18
	v_mov_b32_e32 v60, v18
	v_mov_b32_e32 v61, v18
	v_mov_b32_e32 v62, v18
	v_mov_b32_e32 v63, v18
	v_mov_b32_e32 v64, v18
	v_mov_b32_e32 v65, v18
	v_mov_b32_e32 v66, v18
	v_mov_b32_e32 v67, v18
	v_mov_b32_e32 v68, v18
	v_mov_b32_e32 v69, v18
	v_mov_b32_e32 v70, v18
	v_mov_b32_e32 v71, v18
	v_mov_b32_e32 v72, v18
	v_mov_b32_e32 v73, v18
	v_mov_b32_e32 v74, v18
	v_mov_b32_e32 v75, v18
	v_mov_b32_e32 v76, v18
	v_mov_b32_e32 v77, v18
	v_mov_b32_e32 v78, v18
	v_mov_b32_e32 v79, v18
	v_mov_b32_e32 v80, v18
	v_mov_b32_e32 v81, v18
	s_mov_b32 s13, 0x7b00000
	s_mov_b32 s17, 0x7e00000
	s_waitcnt lgkmcnt(0)
	s_barrier
	s_branch .LBB0_76
